# final RMSNorm output stores non-temporal (the output is never re-read by the kernel)
# speedup vs baseline: 1.0032x; 1.0031x over previous
.LBB0_961:
	s_or_b64 exec, exec, s[18:19]
	s_waitcnt vmcnt(12)
	ds_bpermute_b32 v65, v54, v64
	s_lshl_b64 s[16:17], s[2:3], 12
	s_waitcnt lgkmcnt(0)
	v_add_f32_e32 v64, v64, v65
	ds_bpermute_b32 v65, v55, v64
	s_waitcnt lgkmcnt(0)
	v_add_f32_e32 v64, v64, v65
	ds_bpermute_b32 v65, v56, v64
	s_waitcnt lgkmcnt(0)
	v_add_f32_e32 v65, v64, v65
	ds_bpermute_b32 v66, v57, v65
	v_lshlrev_b32_e32 v64, 16, v52
	s_waitcnt lgkmcnt(0)
	v_add_f32_e32 v65, v65, v66
	ds_bpermute_b32 v67, v58, v65
	v_and_b32_e32 v65, 0xffff0000, v52
	v_lshlrev_b32_e32 v52, 16, v53
	v_and_b32_e32 v53, 0xffff0000, v53
	v_lshlrev_b32_e32 v66, 16, v50
	s_waitcnt lgkmcnt(0)
	v_fmamk_f32 v67, v67, 0x3a800000, v59
	v_mul_f32_e32 v68, 0x4f800000, v67
	v_cmp_gt_f32_e32 vcc, s21, v67
	s_nop 1
	v_cndmask_b32_e32 v68, v67, v68, vcc
	v_sqrt_f32_e32 v69, v68
	v_and_b32_e32 v67, 0xffff0000, v50
	v_lshlrev_b32_e32 v50, 16, v51
	v_and_b32_e32 v51, 0xffff0000, v51
	v_add_u32_e32 v70, -1, v69
	v_add_u32_e32 v71, 1, v69
	v_fma_f32 v72, -v70, v69, v68
	v_fma_f32 v73, -v71, v69, v68
	v_cmp_ge_f32_e64 s[2:3], 0, v72
	s_nop 1
	v_cndmask_b32_e64 v69, v69, v70, s[2:3]
	v_cmp_lt_f32_e64 s[2:3], 0, v73
	s_nop 1
	v_cndmask_b32_e64 v69, v69, v71, s[2:3]
	v_mul_f32_e32 v70, 0x37800000, v69
	v_cndmask_b32_e32 v69, v69, v70, vcc
	v_cmp_class_f32_e32 vcc, v68, v60
	s_nop 1
	v_cndmask_b32_e32 v70, v69, v68, vcc
	v_div_scale_f32 v71, s[2:3], v70, v70, 1.0
	v_rcp_f32_e32 v72, v71
	v_div_scale_f32 v73, vcc, 1.0, v70, 1.0
	v_lshl_add_u64 v[68:69], v[20:21], 0, s[16:17]
	v_fma_f32 v74, -v71, v72, 1.0
	v_fmac_f32_e32 v72, v74, v72
	v_mul_f32_e32 v74, v73, v72
	v_fma_f32 v75, -v71, v74, v73
	v_fmac_f32_e32 v74, v75, v72
	v_fma_f32 v71, -v71, v74, v73
	v_div_fmas_f32 v71, v71, v72, v74
	v_div_fixup_f32 v70, v71, v70, 1.0
	v_pk_mul_f32 v[64:65], v[70:71], v[64:65] op_sel_hi:[0,1]
	v_pk_mul_f32 v[52:53], v[70:71], v[52:53] op_sel_hi:[0,1]
	v_pk_mul_f32 v[72:73], v[70:71], v[66:67] op_sel_hi:[0,1]
	v_pk_mul_f32 v[66:67], v[70:71], v[50:51] op_sel_hi:[0,1]
	v_pk_mul_f32 v[52:53], v[2:3], v[52:53]
	v_pk_mul_f32 v[50:51], v[0:1], v[64:65]
	v_pk_mul_f32 v[66:67], v[6:7], v[66:67]
	v_pk_mul_f32 v[64:65], v[4:5], v[72:73]
	global_store_dwordx4 v[68:69], v[50:53], off nt
	global_store_dwordx4 v[68:69], v[64:67], off offset:1024 nt
	s_andn2_b64 vcc, exec, s[14:15]
	v_lshlrev_b32_e32 v50, 16, v48
	v_and_b32_e32 v51, 0xffff0000, v48
	v_lshlrev_b32_e32 v48, 16, v49
	v_and_b32_e32 v49, 0xffff0000, v49
	v_pk_mul_f32 v[52:53], v[70:71], v[50:51] op_sel_hi:[0,1]
	v_pk_mul_f32 v[48:49], v[70:71], v[48:49] op_sel_hi:[0,1]
	v_pk_mul_f32 v[50:51], v[10:11], v[48:49]
	v_pk_mul_f32 v[48:49], v[8:9], v[52:53]
	global_store_dwordx4 v[68:69], v[48:51], off offset:2048 nt
	s_nop 1
	v_lshlrev_b32_e32 v48, 16, v46
	v_and_b32_e32 v49, 0xffff0000, v46
	v_lshlrev_b32_e32 v46, 16, v47
	v_and_b32_e32 v47, 0xffff0000, v47
	v_pk_mul_f32 v[50:51], v[70:71], v[48:49] op_sel_hi:[0,1]
	v_pk_mul_f32 v[46:47], v[70:71], v[46:47] op_sel_hi:[0,1]
	v_pk_mul_f32 v[48:49], v[14:15], v[46:47]
	v_pk_mul_f32 v[46:47], v[12:13], v[50:51]
	global_store_dwordx4 v[68:69], v[46:49], off offset:3072 nt
	s_cbranch_vccnz .LBB0_964
	s_waitcnt vmcnt(12)
	ds_bpermute_b32 v46, v54, v63
	s_ashr_i32 s5, s4, 31
	s_lshl_b64 s[14:15], s[4:5], 12
	s_waitcnt lgkmcnt(0)
	v_add_f32_e32 v46, v63, v46
	ds_bpermute_b32 v47, v55, v46
	s_waitcnt lgkmcnt(0)
	v_add_f32_e32 v46, v46, v47
	ds_bpermute_b32 v47, v56, v46
	s_waitcnt lgkmcnt(0)
	v_add_f32_e32 v48, v46, v47
	ds_bpermute_b32 v49, v57, v48
	v_lshlrev_b32_e32 v46, 16, v44
	v_and_b32_e32 v47, 0xffff0000, v44
	s_waitcnt lgkmcnt(0)
	v_add_f32_e32 v44, v48, v49
	ds_bpermute_b32 v50, v58, v44
	v_lshlrev_b32_e32 v48, 16, v42
	v_and_b32_e32 v49, 0xffff0000, v42
	v_lshlrev_b32_e32 v44, 16, v45
	v_and_b32_e32 v45, 0xffff0000, v45
	s_waitcnt lgkmcnt(0)
	v_fmamk_f32 v42, v50, 0x3a800000, v59
	v_mul_f32_e32 v50, 0x4f800000, v42
	v_cmp_gt_f32_e32 vcc, s21, v42
	s_nop 1
	v_cndmask_b32_e32 v50, v42, v50, vcc
	v_sqrt_f32_e32 v51, v50
	v_lshlrev_b32_e32 v42, 16, v43
	v_and_b32_e32 v43, 0xffff0000, v43
	v_add_u32_e32 v52, -1, v51
	v_add_u32_e32 v53, 1, v51
	v_fma_f32 v63, -v52, v51, v50
	v_fma_f32 v64, -v53, v51, v50
	v_cmp_ge_f32_e64 s[2:3], 0, v63
	s_nop 1
	v_cndmask_b32_e64 v51, v51, v52, s[2:3]
	v_cmp_lt_f32_e64 s[2:3], 0, v64
	s_nop 1
	v_cndmask_b32_e64 v51, v51, v53, s[2:3]
	v_mul_f32_e32 v52, 0x37800000, v51
	v_cndmask_b32_e32 v51, v51, v52, vcc
	v_cmp_class_f32_e32 vcc, v50, v60
	s_nop 1
	v_cndmask_b32_e32 v52, v51, v50, vcc
	v_div_scale_f32 v53, s[2:3], v52, v52, 1.0
	v_rcp_f32_e32 v63, v53
	v_div_scale_f32 v64, vcc, 1.0, v52, 1.0
	v_lshl_add_u64 v[50:51], v[20:21], 0, s[14:15]
	v_fma_f32 v65, -v53, v63, 1.0
	v_fmac_f32_e32 v63, v65, v63
	v_mul_f32_e32 v65, v64, v63
	v_fma_f32 v66, -v53, v65, v64
	v_fmac_f32_e32 v65, v66, v63
	v_fma_f32 v53, -v53, v65, v64
	v_div_fmas_f32 v53, v53, v63, v65
	v_div_fixup_f32 v52, v53, v52, 1.0
	v_pk_mul_f32 v[46:47], v[52:53], v[46:47] op_sel_hi:[0,1]
	v_pk_mul_f32 v[44:45], v[52:53], v[44:45] op_sel_hi:[0,1]
	v_pk_mul_f32 v[48:49], v[52:53], v[48:49] op_sel_hi:[0,1]
	v_pk_mul_f32 v[64:65], v[52:53], v[42:43] op_sel_hi:[0,1]
	v_pk_mul_f32 v[44:45], v[2:3], v[44:45]
	v_pk_mul_f32 v[42:43], v[0:1], v[46:47]
	v_pk_mul_f32 v[46:47], v[6:7], v[64:65]
	global_store_dwordx4 v[50:51], v[42:45], off nt
	s_nop 1
	v_pk_mul_f32 v[44:45], v[4:5], v[48:49]
	v_lshlrev_b32_e32 v42, 16, v40
	v_and_b32_e32 v43, 0xffff0000, v40
	v_lshlrev_b32_e32 v40, 16, v41
	v_and_b32_e32 v41, 0xffff0000, v41
	global_store_dwordx4 v[50:51], v[44:47], off offset:1024 nt
	v_pk_mul_f32 v[40:41], v[52:53], v[40:41] op_sel_hi:[0,1]
	s_nop 0
	v_pk_mul_f32 v[44:45], v[52:53], v[42:43] op_sel_hi:[0,1]
	v_pk_mul_f32 v[42:43], v[10:11], v[40:41]
	v_pk_mul_f32 v[40:41], v[8:9], v[44:45]
	global_store_dwordx4 v[50:51], v[40:43], off offset:2048 nt
	s_nop 1
	v_lshlrev_b32_e32 v40, 16, v38
	v_and_b32_e32 v41, 0xffff0000, v38
	v_lshlrev_b32_e32 v38, 16, v39
	v_and_b32_e32 v39, 0xffff0000, v39
	v_pk_mul_f32 v[42:43], v[52:53], v[40:41] op_sel_hi:[0,1]
	v_pk_mul_f32 v[38:39], v[52:53], v[38:39] op_sel_hi:[0,1]
	v_pk_mul_f32 v[40:41], v[14:15], v[38:39]
	v_pk_mul_f32 v[38:39], v[12:13], v[42:43]
	global_store_dwordx4 v[50:51], v[38:41], off offset:3072 nt
	s_andn2_b64 vcc, exec, s[12:13]
	s_cbranch_vccz .LBB0_965

.LBB0_965:
	s_waitcnt vmcnt(8)
	ds_bpermute_b32 v38, v54, v62
	s_ashr_i32 s11, s10, 31
	s_lshl_b64 s[10:11], s[10:11], 12
	s_waitcnt lgkmcnt(0)
	v_add_f32_e32 v38, v62, v38
	ds_bpermute_b32 v39, v55, v38
	s_waitcnt lgkmcnt(0)
	v_add_f32_e32 v38, v38, v39
	ds_bpermute_b32 v39, v56, v38
	s_waitcnt lgkmcnt(0)
	v_add_f32_e32 v40, v38, v39
	ds_bpermute_b32 v41, v57, v40
	v_lshlrev_b32_e32 v38, 16, v36
	v_and_b32_e32 v39, 0xffff0000, v36
	s_waitcnt lgkmcnt(0)
	v_add_f32_e32 v36, v40, v41
	ds_bpermute_b32 v42, v58, v36
	v_lshlrev_b32_e32 v40, 16, v34
	v_and_b32_e32 v41, 0xffff0000, v34
	v_lshlrev_b32_e32 v36, 16, v37
	v_and_b32_e32 v37, 0xffff0000, v37
	s_waitcnt lgkmcnt(0)
	v_fmamk_f32 v34, v42, 0x3a800000, v59
	v_mul_f32_e32 v42, 0x4f800000, v34
	v_cmp_gt_f32_e32 vcc, s21, v34
	s_nop 1
	v_cndmask_b32_e32 v42, v34, v42, vcc
	v_sqrt_f32_e32 v43, v42
	v_lshlrev_b32_e32 v34, 16, v35
	v_and_b32_e32 v35, 0xffff0000, v35
	v_add_u32_e32 v44, -1, v43
	v_add_u32_e32 v45, 1, v43
	v_fma_f32 v46, -v44, v43, v42
	v_fma_f32 v47, -v45, v43, v42
	v_cmp_ge_f32_e64 s[2:3], 0, v46
	s_nop 1
	v_cndmask_b32_e64 v43, v43, v44, s[2:3]
	v_cmp_lt_f32_e64 s[2:3], 0, v47
	s_nop 1
	v_cndmask_b32_e64 v43, v43, v45, s[2:3]
	v_mul_f32_e32 v44, 0x37800000, v43
	v_cndmask_b32_e32 v43, v43, v44, vcc
	v_cmp_class_f32_e32 vcc, v42, v60
	s_nop 1
	v_cndmask_b32_e32 v44, v43, v42, vcc
	v_div_scale_f32 v45, s[2:3], v44, v44, 1.0
	v_rcp_f32_e32 v46, v45
	v_div_scale_f32 v47, vcc, 1.0, v44, 1.0
	v_lshl_add_u64 v[42:43], v[20:21], 0, s[10:11]
	v_fma_f32 v48, -v45, v46, 1.0
	v_fmac_f32_e32 v46, v48, v46
	v_mul_f32_e32 v48, v47, v46
	v_fma_f32 v49, -v45, v48, v47
	v_fmac_f32_e32 v48, v49, v46
	v_fma_f32 v45, -v45, v48, v47
	v_div_fmas_f32 v45, v45, v46, v48
	v_div_fixup_f32 v44, v45, v44, 1.0
	v_pk_mul_f32 v[38:39], v[44:45], v[38:39] op_sel_hi:[0,1]
	v_pk_mul_f32 v[36:37], v[44:45], v[36:37] op_sel_hi:[0,1]
	v_pk_mul_f32 v[40:41], v[44:45], v[40:41] op_sel_hi:[0,1]
	v_pk_mul_f32 v[46:47], v[44:45], v[34:35] op_sel_hi:[0,1]
	v_pk_mul_f32 v[36:37], v[2:3], v[36:37]
	v_pk_mul_f32 v[34:35], v[0:1], v[38:39]
	v_pk_mul_f32 v[38:39], v[6:7], v[46:47]
	global_store_dwordx4 v[42:43], v[34:37], off nt
	s_nop 1
	v_pk_mul_f32 v[36:37], v[4:5], v[40:41]
	v_lshlrev_b32_e32 v34, 16, v32
	v_and_b32_e32 v35, 0xffff0000, v32
	v_lshlrev_b32_e32 v32, 16, v33
	v_and_b32_e32 v33, 0xffff0000, v33
	global_store_dwordx4 v[42:43], v[36:39], off offset:1024 nt
	v_pk_mul_f32 v[32:33], v[44:45], v[32:33] op_sel_hi:[0,1]
	s_nop 0
	v_pk_mul_f32 v[36:37], v[44:45], v[34:35] op_sel_hi:[0,1]
	v_pk_mul_f32 v[34:35], v[10:11], v[32:33]
	v_pk_mul_f32 v[32:33], v[8:9], v[36:37]
	global_store_dwordx4 v[42:43], v[32:35], off offset:2048 nt
	s_nop 1
	v_lshlrev_b32_e32 v32, 16, v30
	v_and_b32_e32 v33, 0xffff0000, v30
	v_lshlrev_b32_e32 v30, 16, v31
	v_and_b32_e32 v31, 0xffff0000, v31
	v_pk_mul_f32 v[34:35], v[44:45], v[32:33] op_sel_hi:[0,1]
	v_pk_mul_f32 v[30:31], v[44:45], v[30:31] op_sel_hi:[0,1]
	v_pk_mul_f32 v[32:33], v[14:15], v[30:31]
	v_pk_mul_f32 v[30:31], v[12:13], v[34:35]
	global_store_dwordx4 v[42:43], v[30:33], off offset:3072 nt
	s_andn2_b64 vcc, exec, s[8:9]
	s_cbranch_vccnz .LBB0_952
.LBB0_966:
	s_waitcnt vmcnt(4)
	ds_bpermute_b32 v30, v54, v61
	s_ashr_i32 s7, s6, 31
	s_lshl_b64 s[6:7], s[6:7], 12
	s_waitcnt lgkmcnt(0)
	v_add_f32_e32 v30, v61, v30
	ds_bpermute_b32 v31, v55, v30
	s_waitcnt lgkmcnt(0)
	v_add_f32_e32 v30, v30, v31
	ds_bpermute_b32 v31, v56, v30
	s_waitcnt lgkmcnt(0)
	v_add_f32_e32 v32, v30, v31
	ds_bpermute_b32 v33, v57, v32
	v_lshlrev_b32_e32 v30, 16, v28
	v_and_b32_e32 v31, 0xffff0000, v28
	s_waitcnt lgkmcnt(0)
	v_add_f32_e32 v28, v32, v33
	ds_bpermute_b32 v34, v58, v28
	v_lshlrev_b32_e32 v32, 16, v26
	v_and_b32_e32 v33, 0xffff0000, v26
	v_lshlrev_b32_e32 v28, 16, v29
	v_and_b32_e32 v29, 0xffff0000, v29
	s_waitcnt lgkmcnt(0)
	v_fmamk_f32 v26, v34, 0x3a800000, v59
	v_mul_f32_e32 v34, 0x4f800000, v26
	v_cmp_gt_f32_e32 vcc, s21, v26
	s_nop 1
	v_cndmask_b32_e32 v34, v26, v34, vcc
	v_sqrt_f32_e32 v35, v34
	v_lshlrev_b32_e32 v26, 16, v27
	v_and_b32_e32 v27, 0xffff0000, v27
	v_add_u32_e32 v36, -1, v35
	v_add_u32_e32 v37, 1, v35
	v_fma_f32 v38, -v36, v35, v34
	v_fma_f32 v39, -v37, v35, v34
	v_cmp_ge_f32_e64 s[2:3], 0, v38
	s_nop 1
	v_cndmask_b32_e64 v35, v35, v36, s[2:3]
	v_cmp_lt_f32_e64 s[2:3], 0, v39
	s_nop 1
	v_cndmask_b32_e64 v35, v35, v37, s[2:3]
	v_mul_f32_e32 v36, 0x37800000, v35
	v_cndmask_b32_e32 v35, v35, v36, vcc
	v_cmp_class_f32_e32 vcc, v34, v60
	s_nop 1
	v_cndmask_b32_e32 v36, v35, v34, vcc
	v_div_scale_f32 v37, s[2:3], v36, v36, 1.0
	v_rcp_f32_e32 v38, v37
	v_div_scale_f32 v39, vcc, 1.0, v36, 1.0
	v_lshl_add_u64 v[34:35], v[20:21], 0, s[6:7]
	v_fma_f32 v40, -v37, v38, 1.0
	v_fmac_f32_e32 v38, v40, v38
	v_mul_f32_e32 v40, v39, v38
	v_fma_f32 v41, -v37, v40, v39
	v_fmac_f32_e32 v40, v41, v38
	v_fma_f32 v37, -v37, v40, v39
	v_div_fmas_f32 v37, v37, v38, v40
	v_div_fixup_f32 v36, v37, v36, 1.0
	v_pk_mul_f32 v[30:31], v[36:37], v[30:31] op_sel_hi:[0,1]
	v_pk_mul_f32 v[28:29], v[36:37], v[28:29] op_sel_hi:[0,1]
	v_pk_mul_f32 v[32:33], v[36:37], v[32:33] op_sel_hi:[0,1]
	v_pk_mul_f32 v[38:39], v[36:37], v[26:27] op_sel_hi:[0,1]
	v_pk_mul_f32 v[28:29], v[2:3], v[28:29]
	v_pk_mul_f32 v[26:27], v[0:1], v[30:31]
	v_pk_mul_f32 v[30:31], v[6:7], v[38:39]
	global_store_dwordx4 v[34:35], v[26:29], off nt
	s_nop 1
	v_pk_mul_f32 v[28:29], v[4:5], v[32:33]
	v_lshlrev_b32_e32 v26, 16, v24
	v_and_b32_e32 v27, 0xffff0000, v24
	v_lshlrev_b32_e32 v24, 16, v25
	v_and_b32_e32 v25, 0xffff0000, v25
	global_store_dwordx4 v[34:35], v[28:31], off offset:1024 nt
	v_pk_mul_f32 v[24:25], v[36:37], v[24:25] op_sel_hi:[0,1]
	s_nop 0
	v_pk_mul_f32 v[28:29], v[36:37], v[26:27] op_sel_hi:[0,1]
	v_pk_mul_f32 v[26:27], v[10:11], v[24:25]
	v_pk_mul_f32 v[24:25], v[8:9], v[28:29]
	global_store_dwordx4 v[34:35], v[24:27], off offset:2048 nt
	s_nop 1
	v_lshlrev_b32_e32 v24, 16, v22
	v_and_b32_e32 v25, 0xffff0000, v22
	v_lshlrev_b32_e32 v22, 16, v23
	v_and_b32_e32 v23, 0xffff0000, v23
	v_pk_mul_f32 v[26:27], v[36:37], v[24:25] op_sel_hi:[0,1]
	v_pk_mul_f32 v[22:23], v[36:37], v[22:23] op_sel_hi:[0,1]
	v_pk_mul_f32 v[24:25], v[14:15], v[22:23]
	v_pk_mul_f32 v[22:23], v[12:13], v[26:27]
	global_store_dwordx4 v[34:35], v[22:25], off offset:3072 nt
	s_branch .LBB0_952
